# combined version + s_setprio 2 while a wave runs the products stage (0 while it runs the next item's TW/AD tiles)
# speedup vs baseline: 1.0011x; 1.0011x over previous
.LBB0_294:
	v_mov_b32_e32 v137, v29
	s_nop 5
	v_cvt_pk_bf16_f32 v48, v78, v79
	v_cvt_pk_bf16_f32 v49, v80, v81
	v_lshl_add_u64 v[26:27], v[26:27], 0, v[136:137]
	global_store_dwordx2 v[26:27], v[48:49], off nt
	v_add_u32_e32 v26, v194, v200
	ds_read_b128 v[78:81], v26
	s_cmp_lg_u32 s51, s72
	s_waitcnt lgkmcnt(0)
	v_mfma_f32_16x16x32_bf16 v[74:77], v[74:77], v[78:81], 0
	ds_read_b128 v[78:81], v26 offset:64
	ds_read_b32 v26, v201
	s_waitcnt lgkmcnt(1)
	v_mfma_f32_16x16x32_bf16 v[70:73], v[70:73], v[78:81], v[74:77]
	s_nop 7
	v_pk_add_f32 v[48:49], v[126:127], v[70:71]
	v_pk_add_f32 v[70:71], v[130:131], v[72:73]
	s_waitcnt lgkmcnt(0)
	v_pk_mul_f32 v[48:49], v[26:27], v[48:49] op_sel_hi:[0,1]
	v_pk_mul_f32 v[26:27], v[26:27], v[70:71] op_sel_hi:[0,1]
	v_cvt_pk_bf16_f32 v48, v48, v49
	v_cvt_pk_bf16_f32 v49, v26, v27
	v_lshl_add_u64 v[26:27], v[124:125], 1, s[26:27]
	global_store_dwordx2 v[26:27], v[48:49], off nt
	v_add_u32_e32 v26, v190, v200
	ds_read_b128 v[70:73], v26
	v_add_u32_e32 v27, v195, v199
	ds_read_b128 v[74:77], v27 offset:10240
	s_waitcnt lgkmcnt(1)
	v_mfma_f32_16x16x32_bf16 v[70:73], v[94:97], v[70:73], 0
	s_waitcnt lgkmcnt(0)
	v_mfma_f32_16x16x32_bf16 v[70:73], v[98:101], v[74:77], v[70:73]
	ds_read_b128 v[74:77], v26 offset:64
	s_waitcnt lgkmcnt(0)
	v_mfma_f32_16x16x32_bf16 v[70:73], v[90:93], v[74:77], v[70:73]
	ds_read_b128 v[74:77], v27 offset:10304
	s_waitcnt lgkmcnt(0)
	v_mfma_f32_16x16x32_bf16 v[70:73], v[86:89], v[74:77], v[70:73]
	s_nop 7
	v_pk_mul_f32 v[26:27], v[68:69], v[72:73]
	v_pk_mul_f32 v[48:49], v[66:67], v[70:71]
	s_nop 0
	v_cvt_pk_bf16_f32 v48, v48, v49
	v_cvt_pk_bf16_f32 v49, v26, v27
	v_lshl_add_u64 v[26:27], v[116:117], 1, s[24:25]
	global_store_dwordx2 v[26:27], v[48:49], off nt
	s_setprio 0
	v_readfirstlane_b32 s36, v0
	s_cmp_lt_u32 s36, 0x100
	s_cbranch_scc1 .Ltw_end
	s_waitcnt vmcnt(8)

.Ltw_prod:
	s_setprio 2
	ds_read_b128 v[74:77], v217
	ds_read_b128 v[78:81], v227
	ds_read_b128 v[70:73], v217 offset:64
	v_add_u32_e32 v26, v192, v196
	ds_read_b128 v[82:85], v228
	ds_read_b128 v[86:89], v26
	ds_read_b128 v[66:69], v204
	s_waitcnt lgkmcnt(1)
	v_mfma_f32_16x16x32_bf16 v[90:93], v[74:77], v[86:89], 0
	v_cndmask_b32_e64 v27, 0, 1, s[62:63]
	v_cmp_ne_u32_e64 s[56:57], 1, v27
	s_cbranch_vccnz .LBB0_397
	ds_read_b128 v[94:97], v26 offset:64
	s_waitcnt lgkmcnt(0)
	v_mfma_f32_16x16x32_bf16 v[90:93], v[70:73], v[94:97], v[90:93]
